# row sum-of-squares lane merges (xor 16 / xor 32) in the P5 and P10 GEMM epilogues via v_permlane16/32_swap instead of ds_bpermute
# baseline (speedup 1.0000x reference)
; DI u32x4 pack8(const f32x4 a, const f32x4 b) { u32x4 w; w.x = pk2(a[0], a[1]); w.y = pk2(a[2], a[3]); w.z = pk2(b[0], b[1]); w.w = pk2(b[2], b[3]); return w; }
; DI float dot4(const f32x4 a) { return (a[0] * a[0] + a[1] * a[1]) + (a[2] * a[2] + a[3] * a[3]); }
; #define EPI_FENCE() asm volatile("" ::: "memory")
;     DI void operator()(const f32x4 (&acc)[2][2][4][2], const Unit& u, int wr, int wc, int fr, int fq) const {
;         const int col0 = u.pn * 256 + wc * 32 + 8 * fq;
;         const int rbase = u.pm * 256 + wr * 64 + fr;
;         u32x4 xw[8][2];
; #pragma unroll
;         for (int i = 0; i < 8; ++i)
; #pragma unroll
;             for (int bj = 0; bj < 2; ++bj) xw[i][bj] = *(const u32x4*)(base + (size_t)(rbase + (i >> 2) * 128 + (i & 3) * 16) * DM + col0 + bj * 128);
;         EPI_FENCE();
; #pragma unroll
;         for (int ai = 0; ai < 2; ++ai)
; #pragma unroll
;             for (int m = 0; m < 4; ++m) {
;                 const int r = rbase + ai * 128 + m * 16;
;                 const size_t off = (size_t)r * DM + col0;
;                 float ss = 0.f;
; #pragma unroll
;                 for (int bj = 0; bj < 2; ++bj) {
;                     const u32x4 w = xw[ai * 4 + m][bj];
;                     const f32x4 v0 = (f32x4){bflo(w.x), bfhi(w.x), bflo(w.y), bfhi(w.y)} + acc[ai][bj][m][0];
;                     const f32x4 v1 = (f32x4){bflo(w.z), bfhi(w.z), bflo(w.w), bfhi(w.w)} + acc[ai][bj][m][1];
;                     *(u32x4*)(xb + off + bj * 128) = pack8(v0, v1); ss += dot4(v0) + dot4(v1);
;                 }
;                 ss += __shfl_xor(ss, 16); ss += __shfl_xor(ss, 32); if (fq == 0) ssq[(size_t)r * 32 + u.pn * 4 + wc] = ss;
;             }
.LBB0_702:
	v_lshl_or_b32 v200, s10, 8, v222
	v_lshl_add_u32 v202, s30, 8, v220
	v_ashrrev_i32_e32 v201, 31, v200
	v_lshlrev_b64 v[238:239], 1, v[200:201]
	v_ashrrev_i32_e32 v203, 31, v202
	v_lshl_add_u64 v[104:105], s[14:15], 0, v[238:239]
	v_lshlrev_b64 v[240:241], 12, v[202:203]
	v_lshl_add_u64 v[106:107], v[104:105], 0, v[240:241]
	global_load_dwordx4 v[230:233], v[106:107], off
	global_load_dwordx4 v[234:237], v[106:107], off offset:256
	v_or_b32_e32 v216, 16, v202
	v_or_b32_e32 v212, 32, v202
	v_or_b32_e32 v208, 48, v202
	v_add_u32_e32 v204, 0x80, v202
	v_add_u32_e32 v116, 0x90, v202
	v_add_u32_e32 v118, 0xa0, v202
	v_add_u32_e32 v128, 0xb0, v202
	v_ashrrev_i32_e32 v217, 31, v216
	v_ashrrev_i32_e32 v213, 31, v212
	v_ashrrev_i32_e32 v209, 31, v208
	v_ashrrev_i32_e32 v205, 31, v204
	v_ashrrev_i32_e32 v117, 31, v116
	v_ashrrev_i32_e32 v119, 31, v118
	v_ashrrev_i32_e32 v129, 31, v128
	v_lshlrev_b64 v[218:219], 12, v[216:217]
	v_lshlrev_b64 v[214:215], 12, v[212:213]
	v_lshlrev_b64 v[210:211], 12, v[208:209]
	v_lshlrev_b64 v[206:207], 12, v[204:205]
	v_lshlrev_b64 v[106:107], 12, v[116:117]
	v_lshlrev_b64 v[116:117], 12, v[118:119]
	v_lshlrev_b64 v[118:119], 12, v[128:129]
	v_lshl_add_u64 v[128:129], v[104:105], 0, v[218:219]
	v_lshl_add_u64 v[130:131], v[104:105], 0, v[214:215]
	v_lshl_add_u64 v[140:141], v[104:105], 0, v[210:211]
	v_lshl_add_u64 v[142:143], v[104:105], 0, v[206:207]
	v_lshl_add_u64 v[106:107], v[104:105], 0, v[106:107]
	v_lshl_add_u64 v[116:117], v[104:105], 0, v[116:117]
	v_lshl_add_u64 v[104:105], v[104:105], 0, v[118:119]
	global_load_dwordx4 v[180:183], v[128:129], off
	global_load_dwordx4 v[176:179], v[128:129], off offset:256
	global_load_dwordx4 v[172:175], v[130:131], off
	global_load_dwordx4 v[168:171], v[130:131], off offset:256
	global_load_dwordx4 v[164:167], v[140:141], off
	global_load_dwordx4 v[160:163], v[140:141], off offset:256
	global_load_dwordx4 v[156:159], v[142:143], off
	global_load_dwordx4 v[152:155], v[142:143], off offset:256
	global_load_dwordx4 v[148:151], v[106:107], off
	global_load_dwordx4 v[144:147], v[106:107], off offset:256
	s_nop 0
	global_load_dwordx4 v[140:143], v[116:117], off
	global_load_dwordx4 v[128:131], v[116:117], off offset:256
	s_nop 0
	global_load_dwordx4 v[116:119], v[104:105], off
	s_nop 0
	global_load_dwordx4 v[104:107], v[104:105], off offset:256
	v_and_b32_e32 v228, 64, v226
	v_xor_b32_e32 v227, 16, v226
	v_add_u32_e32 v228, 64, v228
	v_xor_b32_e32 v229, 32, v226
	v_cmp_lt_i32_e32 vcc, v227, v228
	s_lshl_b32 s30, s10, 2
	s_ashr_i32 s31, s30, 31
	v_cndmask_b32_e32 v227, v226, v227, vcc
	v_cmp_lt_i32_e32 vcc, v229, v228
	v_lshlrev_b32_e32 v228, 2, v227
	s_waitcnt vmcnt(0)
	v_lshlrev_b32_e32 v242, 16, v230
	v_and_b32_e32 v243, 0xffff0000, v230
	v_lshlrev_b32_e32 v230, 16, v231
	v_and_b32_e32 v231, 0xffff0000, v231
	v_lshlrev_b32_e32 v244, 16, v232
	v_and_b32_e32 v245, 0xffff0000, v232
	v_lshlrev_b32_e32 v232, 16, v233
	v_and_b32_e32 v233, 0xffff0000, v233
	v_cndmask_b32_e32 v229, v226, v229, vcc
	v_pk_add_f32 v[138:139], v[138:139], v[230:231]
	v_pk_add_f32 v[136:137], v[136:137], v[242:243]
	v_pk_add_f32 v[230:231], v[134:135], v[232:233]
	v_pk_add_f32 v[232:233], v[132:133], v[244:245]
	v_lshlrev_b32_e32 v227, 2, v229
	v_cvt_pk_bf16_f32 v132, v136, v137
	v_cvt_pk_bf16_f32 v133, v138, v139
	v_cvt_pk_bf16_f32 v135, v230, v231
	v_mul_f32_e32 v137, v137, v137
	v_mul_f32_e32 v139, v139, v139
	v_mul_f32_e32 v229, v233, v233
	v_mul_f32_e32 v231, v231, v231
	v_fmac_f32_e32 v137, v136, v136
	v_fmac_f32_e32 v139, v138, v138
	v_fmac_f32_e32 v229, v232, v232
	v_fmac_f32_e32 v231, v230, v230
	v_add_f32_e32 v136, v137, v139
	v_add_f32_e32 v137, v229, v231
	v_add_f32_e32 v229, v136, v137
	v_lshlrev_b32_e32 v136, 16, v234
	v_and_b32_e32 v137, 0xffff0000, v234
	v_lshlrev_b32_e32 v138, 16, v235
	v_and_b32_e32 v139, 0xffff0000, v235
	v_pk_add_f32 v[126:127], v[126:127], v[138:139]
	v_pk_add_f32 v[124:125], v[124:125], v[136:137]
	v_lshlrev_b32_e32 v136, 16, v236
	v_and_b32_e32 v137, 0xffff0000, v236
	v_lshlrev_b32_e32 v138, 16, v237
	v_and_b32_e32 v139, 0xffff0000, v237
	v_pk_add_f32 v[136:137], v[120:121], v[136:137]
	v_mul_f32_e32 v120, v125, v125
	v_mul_f32_e32 v121, v127, v127
	v_pk_add_f32 v[138:139], v[122:123], v[138:139]
	v_fmac_f32_e32 v120, v124, v124
	v_fmac_f32_e32 v121, v126, v126
	v_add_f32_e32 v120, v120, v121
	v_mul_f32_e32 v121, v137, v137
	v_mul_f32_e32 v122, v139, v139
	v_fmac_f32_e32 v121, v136, v136
	v_fmac_f32_e32 v122, v138, v138
	v_add_f32_e32 v121, v121, v122
	v_add_f32_e32 v120, v120, v121
	v_add_f32_e32 v123, v229, v120
	v_mov_b32_e32 v229, v123
	s_nop 1
	v_permlane16_swap_b32_e32 v229, v123
	v_lshl_add_u64 v[120:121], s[62:63], 0, v[240:241]
	v_lshl_add_u64 v[230:231], v[120:121], 0, v[238:239]
	v_cvt_pk_bf16_f32 v134, v232, v233
	v_cvt_pk_bf16_f32 v122, v124, v125
	s_waitcnt lgkmcnt(0)
	v_add_f32_e32 v120, v123, v229
	v_mov_b32_e32 v121, v120
	s_nop 1
	v_permlane32_swap_b32_e32 v121, v120
	v_cvt_pk_bf16_f32 v123, v126, v127
	v_cvt_pk_bf16_f32 v124, v136, v137
	v_cvt_pk_bf16_f32 v125, v138, v139
	global_store_dwordx4 v[230:231], v[132:135], off
	global_store_dwordx4 v[230:231], v[122:125], off offset:256
	s_and_saveexec_b64 s[34:35], s[4:5]
	s_cbranch_execz .LBB0_704
	v_lshlrev_b64 v[122:123], 7, v[202:203]
	v_lshl_add_u64 v[122:123], s[0:1], 0, v[122:123]
	v_lshl_add_u64 v[122:123], s[30:31], 2, v[122:123]
	s_lshl_b32 s10, s46, 2
	v_lshl_add_u64 v[122:123], v[122:123], 0, s[10:11]
	s_waitcnt lgkmcnt(0)
	v_add_f32_e32 v120, v120, v121
	global_store_dword v[122:123], v120, off
; DI u32x4 pack8(const f32x4 a, const f32x4 b) { u32x4 w; w.x = pk2(a[0], a[1]); w.y = pk2(a[2], a[3]); w.z = pk2(b[0], b[1]); w.w = pk2(b[2], b[3]); return w; }
; DI float dot4(const f32x4 a) { return (a[0] * a[0] + a[1] * a[1]) + (a[2] * a[2] + a[3] * a[3]); }
;     DI void operator()(const f32x4 (&acc)[2][2][4][2], const Unit& u, int wr, int wc, int fr, int fq) const {
;     ...
;         for (int ai = 0; ai < 2; ++ai)
; #pragma unroll
;             for (int m = 0; m < 4; ++m) {
;                 const int r = rbase + ai * 128 + m * 16;
;                 const size_t off = (size_t)r * DM + col0;
;                 float ss = 0.f;
; #pragma unroll
;                 for (int bj = 0; bj < 2; ++bj) {
;                     const u32x4 w = xw[ai * 4 + m][bj];
;                     const f32x4 v0 = (f32x4){bflo(w.x), bfhi(w.x), bflo(w.y), bfhi(w.y)} + acc[ai][bj][m][0];
;                     const f32x4 v1 = (f32x4){bflo(w.z), bfhi(w.z), bflo(w.w), bfhi(w.w)} + acc[ai][bj][m][1];
;                     *(u32x4*)(xb + off + bj * 128) = pack8(v0, v1); ss += dot4(v0) + dot4(v1);
;                 }
;                 ss += __shfl_xor(ss, 16); ss += __shfl_xor(ss, 32); if (fq == 0) ssq[(size_t)r * 32 + u.pn * 4 + wc] = ss;
;             }
.LBB0_704:
	s_or_b64 exec, exec, s[34:35]
	v_lshlrev_b32_e32 v120, 16, v180
	s_waitcnt lgkmcnt(0)
	v_and_b32_e32 v121, 0xffff0000, v180
	v_lshlrev_b32_e32 v122, 16, v181
	v_and_b32_e32 v123, 0xffff0000, v181
	v_pk_add_f32 v[112:113], v[112:113], v[120:121]
	v_lshlrev_b32_e32 v120, 16, v182
	v_and_b32_e32 v121, 0xffff0000, v182
	v_pk_add_f32 v[114:115], v[114:115], v[122:123]
	v_pk_add_f32 v[120:121], v[108:109], v[120:121]
	v_cvt_pk_bf16_f32 v108, v112, v113
	v_mul_f32_e32 v113, v113, v113
	v_lshlrev_b32_e32 v122, 16, v183
	v_and_b32_e32 v123, 0xffff0000, v183
	v_fmac_f32_e32 v113, v112, v112
	v_mul_f32_e32 v112, v115, v115
	v_pk_add_f32 v[122:123], v[110:111], v[122:123]
	v_fmac_f32_e32 v112, v114, v114
	v_cvt_pk_bf16_f32 v109, v114, v115
	v_add_f32_e32 v112, v113, v112
	v_mul_f32_e32 v113, v121, v121
	v_mul_f32_e32 v114, v123, v123
	v_fmac_f32_e32 v113, v120, v120
	v_fmac_f32_e32 v114, v122, v122
	v_add_f32_e32 v113, v113, v114
	v_cvt_pk_bf16_f32 v110, v120, v121
	v_add_f32_e32 v120, v112, v113
	v_lshlrev_b32_e32 v112, 16, v176
	v_and_b32_e32 v113, 0xffff0000, v176
	v_lshlrev_b32_e32 v114, 16, v177
	v_and_b32_e32 v115, 0xffff0000, v177
	v_pk_add_f32 v[102:103], v[102:103], v[114:115]
	v_pk_add_f32 v[100:101], v[100:101], v[112:113]
	v_lshlrev_b32_e32 v112, 16, v178
	v_and_b32_e32 v113, 0xffff0000, v178
	v_lshlrev_b32_e32 v114, 16, v179
	v_and_b32_e32 v115, 0xffff0000, v179
	v_pk_add_f32 v[112:113], v[96:97], v[112:113]
	v_mul_f32_e32 v96, v101, v101
	v_mul_f32_e32 v97, v103, v103
	v_pk_add_f32 v[114:115], v[98:99], v[114:115]
	v_fmac_f32_e32 v96, v100, v100
	v_fmac_f32_e32 v97, v102, v102
	v_add_f32_e32 v96, v96, v97
	v_mul_f32_e32 v97, v113, v113
	v_mul_f32_e32 v98, v115, v115
	v_fmac_f32_e32 v97, v112, v112
	v_fmac_f32_e32 v98, v114, v114
	v_add_f32_e32 v97, v97, v98
	v_add_f32_e32 v96, v96, v97
	v_add_f32_e32 v99, v120, v96
	v_cvt_pk_bf16_f32 v111, v122, v123
	v_mov_b32_e32 v122, v99
	s_nop 1
	v_permlane16_swap_b32_e32 v122, v99
	v_lshl_add_u64 v[96:97], s[62:63], 0, v[218:219]
	v_lshl_add_u64 v[120:121], v[200:201], 1, v[96:97]
	v_cvt_pk_bf16_f32 v98, v100, v101
	v_cvt_pk_bf16_f32 v100, v112, v113
	s_waitcnt lgkmcnt(0)
	v_add_f32_e32 v96, v99, v122
	v_mov_b32_e32 v97, v96
	s_nop 1
	v_permlane32_swap_b32_e32 v97, v96
	v_cvt_pk_bf16_f32 v99, v102, v103
	v_cvt_pk_bf16_f32 v101, v114, v115
	global_store_dwordx4 v[120:121], v[108:111], off
	global_store_dwordx4 v[120:121], v[98:101], off offset:256
	s_and_saveexec_b64 s[34:35], s[4:5]
	s_cbranch_execz .LBB0_706
	v_lshlrev_b64 v[98:99], 7, v[216:217]
	v_lshl_add_u64 v[98:99], s[0:1], 0, v[98:99]
	v_lshl_add_u64 v[98:99], s[30:31], 2, v[98:99]
	s_lshl_b32 s10, s46, 2
	v_lshl_add_u64 v[98:99], v[98:99], 0, s[10:11]
	s_waitcnt lgkmcnt(0)
	v_add_f32_e32 v96, v96, v97
	global_store_dword v[98:99], v96, off
.LBB0_706:
	s_or_b64 exec, exec, s[34:35]
	v_lshlrev_b32_e32 v96, 16, v172
	s_waitcnt lgkmcnt(0)
	v_and_b32_e32 v97, 0xffff0000, v172
	v_lshlrev_b32_e32 v98, 16, v173
	v_and_b32_e32 v99, 0xffff0000, v173
	v_pk_add_f32 v[92:93], v[92:93], v[96:97]
	v_lshlrev_b32_e32 v96, 16, v174
	v_and_b32_e32 v97, 0xffff0000, v174
	v_pk_add_f32 v[94:95], v[94:95], v[98:99]
	v_pk_add_f32 v[96:97], v[88:89], v[96:97]
	v_cvt_pk_bf16_f32 v88, v92, v93
	v_mul_f32_e32 v93, v93, v93
	v_lshlrev_b32_e32 v98, 16, v175
	v_and_b32_e32 v99, 0xffff0000, v175
	v_fmac_f32_e32 v93, v92, v92
	v_mul_f32_e32 v92, v95, v95
	v_pk_add_f32 v[98:99], v[90:91], v[98:99]
	v_fmac_f32_e32 v92, v94, v94
	v_cvt_pk_bf16_f32 v89, v94, v95
	v_add_f32_e32 v92, v93, v92
	v_mul_f32_e32 v93, v97, v97
	v_mul_f32_e32 v94, v99, v99
	v_fmac_f32_e32 v93, v96, v96
	v_fmac_f32_e32 v94, v98, v98
	v_add_f32_e32 v93, v93, v94
	v_cvt_pk_bf16_f32 v90, v96, v97
	v_add_f32_e32 v96, v92, v93
	v_lshlrev_b32_e32 v92, 16, v168
	v_and_b32_e32 v93, 0xffff0000, v168
	v_lshlrev_b32_e32 v94, 16, v169
	v_and_b32_e32 v95, 0xffff0000, v169
	v_pk_add_f32 v[86:87], v[86:87], v[94:95]
	v_pk_add_f32 v[84:85], v[84:85], v[92:93]
	v_lshlrev_b32_e32 v92, 16, v170
	v_and_b32_e32 v93, 0xffff0000, v170
	v_lshlrev_b32_e32 v94, 16, v171
	v_and_b32_e32 v95, 0xffff0000, v171
	v_pk_add_f32 v[92:93], v[80:81], v[92:93]
	v_mul_f32_e32 v80, v85, v85
	v_mul_f32_e32 v81, v87, v87
	v_pk_add_f32 v[94:95], v[82:83], v[94:95]
	v_fmac_f32_e32 v80, v84, v84
	v_fmac_f32_e32 v81, v86, v86
	v_add_f32_e32 v80, v80, v81
	v_mul_f32_e32 v81, v93, v93
	v_mul_f32_e32 v82, v95, v95
	v_fmac_f32_e32 v81, v92, v92
	v_fmac_f32_e32 v82, v94, v94
	v_add_f32_e32 v81, v81, v82
	v_add_f32_e32 v80, v80, v81
	v_add_f32_e32 v83, v96, v80
	v_cvt_pk_bf16_f32 v91, v98, v99
	v_mov_b32_e32 v98, v83
	s_nop 1
	v_permlane16_swap_b32_e32 v98, v83
	v_lshl_add_u64 v[80:81], s[62:63], 0, v[214:215]
	v_lshl_add_u64 v[96:97], v[200:201], 1, v[80:81]
	v_cvt_pk_bf16_f32 v82, v84, v85
	v_cvt_pk_bf16_f32 v84, v92, v93
	s_waitcnt lgkmcnt(0)
	v_add_f32_e32 v80, v83, v98
	v_mov_b32_e32 v81, v80
	s_nop 1
	v_permlane32_swap_b32_e32 v81, v80
	v_cvt_pk_bf16_f32 v83, v86, v87
	v_cvt_pk_bf16_f32 v85, v94, v95
	global_store_dwordx4 v[96:97], v[88:91], off
	global_store_dwordx4 v[96:97], v[82:85], off offset:256
	s_and_saveexec_b64 s[34:35], s[4:5]
	s_cbranch_execz .LBB0_708
	v_lshlrev_b64 v[82:83], 7, v[212:213]
	v_lshl_add_u64 v[82:83], s[0:1], 0, v[82:83]
	v_lshl_add_u64 v[82:83], s[30:31], 2, v[82:83]
	s_lshl_b32 s10, s46, 2
	v_lshl_add_u64 v[82:83], v[82:83], 0, s[10:11]
	s_waitcnt lgkmcnt(0)
	v_add_f32_e32 v80, v80, v81
	global_store_dword v[82:83], v80, off
; DI u32x4 pack8(const f32x4 a, const f32x4 b) { u32x4 w; w.x = pk2(a[0], a[1]); w.y = pk2(a[2], a[3]); w.z = pk2(b[0], b[1]); w.w = pk2(b[2], b[3]); return w; }
; DI float dot4(const f32x4 a) { return (a[0] * a[0] + a[1] * a[1]) + (a[2] * a[2] + a[3] * a[3]); }
;     DI void operator()(const f32x4 (&acc)[2][2][4][2], const Unit& u, int wr, int wc, int fr, int fq) const {
;     ...
;         for (int ai = 0; ai < 2; ++ai)
; #pragma unroll
;             for (int m = 0; m < 4; ++m) {
;                 const int r = rbase + ai * 128 + m * 16;
;                 const size_t off = (size_t)r * DM + col0;
;                 float ss = 0.f;
; #pragma unroll
;                 for (int bj = 0; bj < 2; ++bj) {
;                     const u32x4 w = xw[ai * 4 + m][bj];
;                     const f32x4 v0 = (f32x4){bflo(w.x), bfhi(w.x), bflo(w.y), bfhi(w.y)} + acc[ai][bj][m][0];
;                     const f32x4 v1 = (f32x4){bflo(w.z), bfhi(w.z), bflo(w.w), bfhi(w.w)} + acc[ai][bj][m][1];
;                     *(u32x4*)(xb + off + bj * 128) = pack8(v0, v1); ss += dot4(v0) + dot4(v1);
;                 }
;                 ss += __shfl_xor(ss, 16); ss += __shfl_xor(ss, 32); if (fq == 0) ssq[(size_t)r * 32 + u.pn * 4 + wc] = ss;
;             }
.LBB0_708:
	s_or_b64 exec, exec, s[34:35]
	v_lshlrev_b32_e32 v80, 16, v164
	s_waitcnt lgkmcnt(0)
	v_and_b32_e32 v81, 0xffff0000, v164
	v_lshlrev_b32_e32 v82, 16, v165
	v_and_b32_e32 v83, 0xffff0000, v165
	v_pk_add_f32 v[76:77], v[76:77], v[80:81]
	v_lshlrev_b32_e32 v80, 16, v166
	v_and_b32_e32 v81, 0xffff0000, v166
	v_pk_add_f32 v[78:79], v[78:79], v[82:83]
	v_pk_add_f32 v[80:81], v[72:73], v[80:81]
	v_cvt_pk_bf16_f32 v72, v76, v77
	v_mul_f32_e32 v77, v77, v77
	v_lshlrev_b32_e32 v82, 16, v167
	v_and_b32_e32 v83, 0xffff0000, v167
	v_fmac_f32_e32 v77, v76, v76
	v_mul_f32_e32 v76, v79, v79
	v_pk_add_f32 v[82:83], v[74:75], v[82:83]
	v_fmac_f32_e32 v76, v78, v78
	v_cvt_pk_bf16_f32 v73, v78, v79
	v_add_f32_e32 v76, v77, v76
	v_mul_f32_e32 v77, v81, v81
	v_mul_f32_e32 v78, v83, v83
	v_fmac_f32_e32 v77, v80, v80
	v_fmac_f32_e32 v78, v82, v82
	v_add_f32_e32 v77, v77, v78
	v_cvt_pk_bf16_f32 v74, v80, v81
	v_add_f32_e32 v80, v76, v77
	v_lshlrev_b32_e32 v76, 16, v160
	v_and_b32_e32 v77, 0xffff0000, v160
	v_lshlrev_b32_e32 v78, 16, v161
	v_and_b32_e32 v79, 0xffff0000, v161
	v_pk_add_f32 v[70:71], v[70:71], v[78:79]
	v_pk_add_f32 v[68:69], v[68:69], v[76:77]
	v_lshlrev_b32_e32 v76, 16, v162
	v_and_b32_e32 v77, 0xffff0000, v162
	v_lshlrev_b32_e32 v78, 16, v163
	v_and_b32_e32 v79, 0xffff0000, v163
	v_pk_add_f32 v[76:77], v[64:65], v[76:77]
	v_mul_f32_e32 v64, v69, v69
	v_mul_f32_e32 v65, v71, v71
	v_pk_add_f32 v[78:79], v[66:67], v[78:79]
	v_fmac_f32_e32 v64, v68, v68
	v_fmac_f32_e32 v65, v70, v70
	v_add_f32_e32 v64, v64, v65
	v_mul_f32_e32 v65, v77, v77
	v_mul_f32_e32 v66, v79, v79
	v_fmac_f32_e32 v65, v76, v76
	v_fmac_f32_e32 v66, v78, v78
	v_add_f32_e32 v65, v65, v66
	v_add_f32_e32 v64, v64, v65
	v_add_f32_e32 v67, v80, v64
	v_cvt_pk_bf16_f32 v75, v82, v83
	v_mov_b32_e32 v82, v67
	s_nop 1
	v_permlane16_swap_b32_e32 v82, v67
	v_lshl_add_u64 v[64:65], s[62:63], 0, v[210:211]
	v_lshl_add_u64 v[80:81], v[200:201], 1, v[64:65]
	v_cvt_pk_bf16_f32 v66, v68, v69
	v_cvt_pk_bf16_f32 v68, v76, v77
	s_waitcnt lgkmcnt(0)
	v_add_f32_e32 v64, v67, v82
	v_mov_b32_e32 v65, v64
	s_nop 1
	v_permlane32_swap_b32_e32 v65, v64
	v_cvt_pk_bf16_f32 v67, v70, v71
	v_cvt_pk_bf16_f32 v69, v78, v79
	global_store_dwordx4 v[80:81], v[72:75], off
	global_store_dwordx4 v[80:81], v[66:69], off offset:256
	s_and_saveexec_b64 s[34:35], s[4:5]
	s_cbranch_execz .LBB0_710
	v_lshlrev_b64 v[66:67], 7, v[208:209]
	v_lshl_add_u64 v[66:67], s[0:1], 0, v[66:67]
	v_lshl_add_u64 v[66:67], s[30:31], 2, v[66:67]
	s_lshl_b32 s10, s46, 2
	v_lshl_add_u64 v[66:67], v[66:67], 0, s[10:11]
	s_waitcnt lgkmcnt(0)
	v_add_f32_e32 v64, v64, v65
	global_store_dword v[66:67], v64, off
.LBB0_710:
	s_or_b64 exec, exec, s[34:35]
	v_lshlrev_b32_e32 v64, 16, v156
	s_waitcnt lgkmcnt(0)
	v_and_b32_e32 v65, 0xffff0000, v156
	v_lshlrev_b32_e32 v66, 16, v157
	v_and_b32_e32 v67, 0xffff0000, v157
	v_pk_add_f32 v[60:61], v[60:61], v[64:65]
	v_lshlrev_b32_e32 v64, 16, v158
	v_and_b32_e32 v65, 0xffff0000, v158
	v_pk_add_f32 v[62:63], v[62:63], v[66:67]
	v_pk_add_f32 v[64:65], v[56:57], v[64:65]
	v_cvt_pk_bf16_f32 v56, v60, v61
	v_mul_f32_e32 v61, v61, v61
	v_lshlrev_b32_e32 v66, 16, v159
	v_and_b32_e32 v67, 0xffff0000, v159
	v_fmac_f32_e32 v61, v60, v60
	v_mul_f32_e32 v60, v63, v63
	v_pk_add_f32 v[66:67], v[58:59], v[66:67]
	v_fmac_f32_e32 v60, v62, v62
	v_cvt_pk_bf16_f32 v57, v62, v63
	v_add_f32_e32 v60, v61, v60
	v_mul_f32_e32 v61, v65, v65
	v_mul_f32_e32 v62, v67, v67
	v_fmac_f32_e32 v61, v64, v64
	v_fmac_f32_e32 v62, v66, v66
	v_add_f32_e32 v61, v61, v62
	v_cvt_pk_bf16_f32 v58, v64, v65
	v_add_f32_e32 v64, v60, v61
	v_lshlrev_b32_e32 v60, 16, v152
	v_and_b32_e32 v61, 0xffff0000, v152
	v_lshlrev_b32_e32 v62, 16, v153
	v_and_b32_e32 v63, 0xffff0000, v153
	v_pk_add_f32 v[54:55], v[54:55], v[62:63]
	v_pk_add_f32 v[52:53], v[52:53], v[60:61]
	v_lshlrev_b32_e32 v60, 16, v154
	v_and_b32_e32 v61, 0xffff0000, v154
	v_lshlrev_b32_e32 v62, 16, v155
	v_and_b32_e32 v63, 0xffff0000, v155
	v_pk_add_f32 v[60:61], v[48:49], v[60:61]
	v_mul_f32_e32 v48, v53, v53
	v_mul_f32_e32 v49, v55, v55
	v_pk_add_f32 v[62:63], v[50:51], v[62:63]
	v_fmac_f32_e32 v48, v52, v52
	v_fmac_f32_e32 v49, v54, v54
	v_add_f32_e32 v48, v48, v49
	v_mul_f32_e32 v49, v61, v61
	v_mul_f32_e32 v50, v63, v63
	v_fmac_f32_e32 v49, v60, v60
	v_fmac_f32_e32 v50, v62, v62
	v_add_f32_e32 v49, v49, v50
	v_add_f32_e32 v48, v48, v49
	v_add_f32_e32 v51, v64, v48
	v_cvt_pk_bf16_f32 v59, v66, v67
	v_mov_b32_e32 v66, v51
	s_nop 1
	v_permlane16_swap_b32_e32 v66, v51
	v_lshl_add_u64 v[48:49], s[62:63], 0, v[206:207]
	v_lshl_add_u64 v[64:65], v[200:201], 1, v[48:49]
	v_cvt_pk_bf16_f32 v50, v52, v53
	v_cvt_pk_bf16_f32 v52, v60, v61
	s_waitcnt lgkmcnt(0)
	v_add_f32_e32 v48, v51, v66
	v_mov_b32_e32 v49, v48
	s_nop 1
	v_permlane32_swap_b32_e32 v49, v48
	v_cvt_pk_bf16_f32 v51, v54, v55
	v_cvt_pk_bf16_f32 v53, v62, v63
	global_store_dwordx4 v[64:65], v[56:59], off
	global_store_dwordx4 v[64:65], v[50:53], off offset:256
	s_and_saveexec_b64 s[34:35], s[4:5]
	s_cbranch_execz .LBB0_712
	v_lshlrev_b64 v[50:51], 7, v[204:205]
	v_lshl_add_u64 v[50:51], s[0:1], 0, v[50:51]
	v_lshl_add_u64 v[50:51], s[30:31], 2, v[50:51]
	s_lshl_b32 s10, s46, 2
	v_lshl_add_u64 v[50:51], v[50:51], 0, s[10:11]
	s_waitcnt lgkmcnt(0)
	v_add_f32_e32 v48, v48, v49
	global_store_dword v[50:51], v48, off
; DI u32x4 pack8(const f32x4 a, const f32x4 b) { u32x4 w; w.x = pk2(a[0], a[1]); w.y = pk2(a[2], a[3]); w.z = pk2(b[0], b[1]); w.w = pk2(b[2], b[3]); return w; }
; DI float dot4(const f32x4 a) { return (a[0] * a[0] + a[1] * a[1]) + (a[2] * a[2] + a[3] * a[3]); }
;     DI void operator()(const f32x4 (&acc)[2][2][4][2], const Unit& u, int wr, int wc, int fr, int fq) const {
;     ...
;         for (int ai = 0; ai < 2; ++ai)
; #pragma unroll
;             for (int m = 0; m < 4; ++m) {
;                 const int r = rbase + ai * 128 + m * 16;
;                 const size_t off = (size_t)r * DM + col0;
;                 float ss = 0.f;
; #pragma unroll
;                 for (int bj = 0; bj < 2; ++bj) {
;                     const u32x4 w = xw[ai * 4 + m][bj];
;                     const f32x4 v0 = (f32x4){bflo(w.x), bfhi(w.x), bflo(w.y), bfhi(w.y)} + acc[ai][bj][m][0];
;                     const f32x4 v1 = (f32x4){bflo(w.z), bfhi(w.z), bflo(w.w), bfhi(w.w)} + acc[ai][bj][m][1];
;                     *(u32x4*)(xb + off + bj * 128) = pack8(v0, v1); ss += dot4(v0) + dot4(v1);
;                 }
;                 ss += __shfl_xor(ss, 16); ss += __shfl_xor(ss, 32); if (fq == 0) ssq[(size_t)r * 32 + u.pn * 4 + wc] = ss;
;             }
.LBB0_712:
	s_or_b64 exec, exec, s[34:35]
	v_lshlrev_b32_e32 v52, 16, v148
	v_and_b32_e32 v53, 0xffff0000, v148
	v_lshlrev_b32_e32 v54, 16, v149
	v_and_b32_e32 v55, 0xffff0000, v149
	v_pk_add_f32 v[44:45], v[44:45], v[52:53]
	v_lshlrev_b32_e32 v52, 16, v150
	v_and_b32_e32 v53, 0xffff0000, v150
	v_pk_add_f32 v[46:47], v[46:47], v[54:55]
	v_pk_add_f32 v[52:53], v[40:41], v[52:53]
	v_cvt_pk_bf16_f32 v40, v44, v45
	v_mul_f32_e32 v45, v45, v45
	v_lshlrev_b32_e32 v54, 16, v151
	v_and_b32_e32 v55, 0xffff0000, v151
	v_fmac_f32_e32 v45, v44, v44
	v_mul_f32_e32 v44, v47, v47
	v_pk_add_f32 v[54:55], v[42:43], v[54:55]
	v_fmac_f32_e32 v44, v46, v46
	v_cvt_pk_bf16_f32 v41, v46, v47
	v_add_f32_e32 v44, v45, v44
	v_mul_f32_e32 v45, v53, v53
	v_mul_f32_e32 v46, v55, v55
	v_fmac_f32_e32 v45, v52, v52
	v_fmac_f32_e32 v46, v54, v54
	v_add_f32_e32 v45, v45, v46
	v_cvt_pk_bf16_f32 v42, v52, v53
	v_add_f32_e32 v52, v44, v45
	v_lshlrev_b32_e32 v44, 16, v144
	v_and_b32_e32 v45, 0xffff0000, v144
	v_lshlrev_b32_e32 v46, 16, v145
	v_and_b32_e32 v47, 0xffff0000, v145
	v_pk_add_f32 v[38:39], v[38:39], v[46:47]
	v_pk_add_f32 v[36:37], v[36:37], v[44:45]
	v_lshlrev_b32_e32 v44, 16, v146
	v_and_b32_e32 v45, 0xffff0000, v146
	v_lshlrev_b32_e32 v46, 16, v147
	v_and_b32_e32 v47, 0xffff0000, v147
	v_pk_add_f32 v[44:45], v[32:33], v[44:45]
	v_mul_f32_e32 v32, v37, v37
	v_mul_f32_e32 v33, v39, v39
	v_pk_add_f32 v[46:47], v[34:35], v[46:47]
	v_fmac_f32_e32 v32, v36, v36
	v_fmac_f32_e32 v33, v38, v38
	v_add_f32_e32 v32, v32, v33
	v_mul_f32_e32 v33, v45, v45
	v_mul_f32_e32 v34, v47, v47
	v_fmac_f32_e32 v33, v44, v44
	v_fmac_f32_e32 v34, v46, v46
	v_add_f32_e32 v33, v33, v34
	v_add_f32_e32 v32, v32, v33
	v_add_f32_e32 v35, v52, v32
	v_mov_b32_e32 v52, v35
	s_nop 1
	v_permlane16_swap_b32_e32 v52, v35
	v_add_u32_e32 v48, 0x90, v202
	s_waitcnt lgkmcnt(1)
	v_ashrrev_i32_e32 v49, 31, v48
	v_lshlrev_b64 v[50:51], 12, v[48:49]
	v_lshl_add_u64 v[32:33], s[62:63], 0, v[50:51]
	v_lshl_add_u64 v[50:51], v[200:201], 1, v[32:33]
	s_waitcnt lgkmcnt(0)
	v_add_f32_e32 v32, v35, v52
	v_mov_b32_e32 v33, v32
	s_nop 1
	v_permlane32_swap_b32_e32 v33, v32
	v_cvt_pk_bf16_f32 v43, v54, v55
	v_cvt_pk_bf16_f32 v34, v36, v37
	v_cvt_pk_bf16_f32 v35, v38, v39
	v_cvt_pk_bf16_f32 v36, v44, v45
	v_cvt_pk_bf16_f32 v37, v46, v47
	global_store_dwordx4 v[50:51], v[40:43], off
	global_store_dwordx4 v[50:51], v[34:37], off offset:256
	s_and_saveexec_b64 s[34:35], s[4:5]
	s_cbranch_execz .LBB0_714
	v_lshlrev_b64 v[34:35], 7, v[48:49]
	v_lshl_add_u64 v[34:35], s[0:1], 0, v[34:35]
	v_lshl_add_u64 v[34:35], s[30:31], 2, v[34:35]
	s_lshl_b32 s10, s46, 2
	v_lshl_add_u64 v[34:35], v[34:35], 0, s[10:11]
	s_waitcnt lgkmcnt(0)
	v_add_f32_e32 v32, v32, v33
	global_store_dword v[34:35], v32, off
; DI u32x4 pack8(const f32x4 a, const f32x4 b) { u32x4 w; w.x = pk2(a[0], a[1]); w.y = pk2(a[2], a[3]); w.z = pk2(b[0], b[1]); w.w = pk2(b[2], b[3]); return w; }
; DI float dot4(const f32x4 a) { return (a[0] * a[0] + a[1] * a[1]) + (a[2] * a[2] + a[3] * a[3]); }
;     DI void operator()(const f32x4 (&acc)[2][2][4][2], const Unit& u, int wr, int wc, int fr, int fq) const {
;     ...
;         for (int ai = 0; ai < 2; ++ai)
; #pragma unroll
;             for (int m = 0; m < 4; ++m) {
;                 const int r = rbase + ai * 128 + m * 16;
;                 const size_t off = (size_t)r * DM + col0;
;                 float ss = 0.f;
; #pragma unroll
;                 for (int bj = 0; bj < 2; ++bj) {
;                     const u32x4 w = xw[ai * 4 + m][bj];
;                     const f32x4 v0 = (f32x4){bflo(w.x), bfhi(w.x), bflo(w.y), bfhi(w.y)} + acc[ai][bj][m][0];
;                     const f32x4 v1 = (f32x4){bflo(w.z), bfhi(w.z), bflo(w.w), bfhi(w.w)} + acc[ai][bj][m][1];
;                     *(u32x4*)(xb + off + bj * 128) = pack8(v0, v1); ss += dot4(v0) + dot4(v1);
;                 }
;                 ss += __shfl_xor(ss, 16); ss += __shfl_xor(ss, 32); if (fq == 0) ssq[(size_t)r * 32 + u.pn * 4 + wc] = ss;
;             }
.LBB0_714:
	s_or_b64 exec, exec, s[34:35]
	v_lshlrev_b32_e32 v36, 16, v140
	v_and_b32_e32 v37, 0xffff0000, v140
	v_lshlrev_b32_e32 v38, 16, v141
	v_and_b32_e32 v39, 0xffff0000, v141
	v_pk_add_f32 v[28:29], v[28:29], v[36:37]
	v_lshlrev_b32_e32 v36, 16, v142
	v_and_b32_e32 v37, 0xffff0000, v142
	v_pk_add_f32 v[30:31], v[30:31], v[38:39]
	v_pk_add_f32 v[36:37], v[24:25], v[36:37]
	v_cvt_pk_bf16_f32 v24, v28, v29
	v_mul_f32_e32 v29, v29, v29
	v_lshlrev_b32_e32 v38, 16, v143
	v_and_b32_e32 v39, 0xffff0000, v143
	v_fmac_f32_e32 v29, v28, v28
	v_mul_f32_e32 v28, v31, v31
	v_pk_add_f32 v[38:39], v[26:27], v[38:39]
	v_fmac_f32_e32 v28, v30, v30
	v_cvt_pk_bf16_f32 v25, v30, v31
	v_add_f32_e32 v28, v29, v28
	v_mul_f32_e32 v29, v37, v37
	v_mul_f32_e32 v30, v39, v39
	v_fmac_f32_e32 v29, v36, v36
	v_fmac_f32_e32 v30, v38, v38
	v_add_f32_e32 v29, v29, v30
	v_cvt_pk_bf16_f32 v26, v36, v37
	v_add_f32_e32 v36, v28, v29
	v_lshlrev_b32_e32 v28, 16, v128
	v_and_b32_e32 v29, 0xffff0000, v128
	v_lshlrev_b32_e32 v30, 16, v129
	v_and_b32_e32 v31, 0xffff0000, v129
	v_pk_add_f32 v[22:23], v[22:23], v[30:31]
	v_pk_add_f32 v[20:21], v[20:21], v[28:29]
	v_lshlrev_b32_e32 v28, 16, v130
	v_and_b32_e32 v29, 0xffff0000, v130
	v_lshlrev_b32_e32 v30, 16, v131
	v_and_b32_e32 v31, 0xffff0000, v131
	v_pk_add_f32 v[28:29], v[16:17], v[28:29]
	v_mul_f32_e32 v16, v21, v21
	v_mul_f32_e32 v17, v23, v23
	v_pk_add_f32 v[30:31], v[18:19], v[30:31]
	v_fmac_f32_e32 v16, v20, v20
	v_fmac_f32_e32 v17, v22, v22
	v_add_f32_e32 v16, v16, v17
	v_mul_f32_e32 v17, v29, v29
	v_mul_f32_e32 v18, v31, v31
	v_fmac_f32_e32 v17, v28, v28
	v_fmac_f32_e32 v18, v30, v30
	v_add_f32_e32 v17, v17, v18
	v_add_f32_e32 v16, v16, v17
	v_add_f32_e32 v19, v36, v16
	v_mov_b32_e32 v36, v19
	s_nop 1
	v_permlane16_swap_b32_e32 v36, v19
	v_add_u32_e32 v32, 0xa0, v202
	s_waitcnt lgkmcnt(1)
	v_ashrrev_i32_e32 v33, 31, v32
	v_lshlrev_b64 v[34:35], 12, v[32:33]
	v_lshl_add_u64 v[16:17], s[62:63], 0, v[34:35]
	v_lshl_add_u64 v[34:35], v[200:201], 1, v[16:17]
	s_waitcnt lgkmcnt(0)
	v_add_f32_e32 v16, v19, v36
	v_mov_b32_e32 v17, v16
	s_nop 1
	v_permlane32_swap_b32_e32 v17, v16
	v_cvt_pk_bf16_f32 v27, v38, v39
	v_cvt_pk_bf16_f32 v18, v20, v21
	v_cvt_pk_bf16_f32 v19, v22, v23
	v_cvt_pk_bf16_f32 v20, v28, v29
	v_cvt_pk_bf16_f32 v21, v30, v31
	global_store_dwordx4 v[34:35], v[24:27], off
	global_store_dwordx4 v[34:35], v[18:21], off offset:256
	s_and_saveexec_b64 s[34:35], s[4:5]
	s_cbranch_execz .LBB0_716
	v_lshlrev_b64 v[18:19], 7, v[32:33]
	v_lshl_add_u64 v[18:19], s[0:1], 0, v[18:19]
	v_lshl_add_u64 v[18:19], s[30:31], 2, v[18:19]
	s_lshl_b32 s10, s46, 2
	v_lshl_add_u64 v[18:19], v[18:19], 0, s[10:11]
	s_waitcnt lgkmcnt(0)
	v_add_f32_e32 v16, v16, v17
	global_store_dword v[18:19], v16, off
.LBB0_716:
	s_or_b64 exec, exec, s[34:35]
	v_lshlrev_b32_e32 v20, 16, v116
	v_and_b32_e32 v21, 0xffff0000, v116
	v_lshlrev_b32_e32 v22, 16, v117
	v_and_b32_e32 v23, 0xffff0000, v117
	v_pk_add_f32 v[12:13], v[12:13], v[20:21]
	v_lshlrev_b32_e32 v20, 16, v118
	v_and_b32_e32 v21, 0xffff0000, v118
	v_pk_add_f32 v[14:15], v[14:15], v[22:23]
	v_pk_add_f32 v[20:21], v[8:9], v[20:21]
	v_cvt_pk_bf16_f32 v8, v12, v13
	v_mul_f32_e32 v13, v13, v13
	v_lshlrev_b32_e32 v22, 16, v119
	v_and_b32_e32 v23, 0xffff0000, v119
	v_fmac_f32_e32 v13, v12, v12
	v_mul_f32_e32 v12, v15, v15
	v_pk_add_f32 v[22:23], v[10:11], v[22:23]
	v_fmac_f32_e32 v12, v14, v14
	v_cvt_pk_bf16_f32 v9, v14, v15
	v_add_f32_e32 v12, v13, v12
	v_mul_f32_e32 v13, v21, v21
	v_mul_f32_e32 v14, v23, v23
	v_fmac_f32_e32 v13, v20, v20
	v_fmac_f32_e32 v14, v22, v22
	v_add_f32_e32 v13, v13, v14
	v_cvt_pk_bf16_f32 v10, v20, v21
	v_add_f32_e32 v20, v12, v13
	v_lshlrev_b32_e32 v12, 16, v104
	v_and_b32_e32 v13, 0xffff0000, v104
	v_lshlrev_b32_e32 v14, 16, v105
	v_and_b32_e32 v15, 0xffff0000, v105
	v_pk_add_f32 v[6:7], v[6:7], v[14:15]
	v_pk_add_f32 v[4:5], v[4:5], v[12:13]
	v_lshlrev_b32_e32 v12, 16, v106
	v_and_b32_e32 v13, 0xffff0000, v106
	v_lshlrev_b32_e32 v14, 16, v107
	v_and_b32_e32 v15, 0xffff0000, v107
	v_pk_add_f32 v[12:13], v[0:1], v[12:13]
	v_mul_f32_e32 v0, v5, v5
	v_mul_f32_e32 v1, v7, v7
	v_pk_add_f32 v[14:15], v[2:3], v[14:15]
	v_fmac_f32_e32 v0, v4, v4
	v_fmac_f32_e32 v1, v6, v6
	v_add_f32_e32 v0, v0, v1
	v_mul_f32_e32 v1, v13, v13
	v_mul_f32_e32 v2, v15, v15
	v_fmac_f32_e32 v1, v12, v12
	v_fmac_f32_e32 v2, v14, v14
	v_add_f32_e32 v1, v1, v2
	v_add_f32_e32 v0, v0, v1
	v_add_f32_e32 v3, v20, v0
	v_mov_b32_e32 v20, v3
	s_nop 1
	v_permlane16_swap_b32_e32 v20, v3
	v_add_u32_e32 v16, 0xb0, v202
	s_waitcnt lgkmcnt(1)
	v_ashrrev_i32_e32 v17, 31, v16
	v_lshlrev_b64 v[18:19], 12, v[16:17]
	v_lshl_add_u64 v[0:1], s[62:63], 0, v[18:19]
	v_lshl_add_u64 v[18:19], v[200:201], 1, v[0:1]
	s_waitcnt lgkmcnt(0)
	v_add_f32_e32 v0, v3, v20
	v_mov_b32_e32 v1, v0
	s_nop 1
	v_permlane32_swap_b32_e32 v1, v0
	v_cvt_pk_bf16_f32 v11, v22, v23
	v_cvt_pk_bf16_f32 v2, v4, v5
	v_cvt_pk_bf16_f32 v3, v6, v7
	v_cvt_pk_bf16_f32 v4, v12, v13
	v_cvt_pk_bf16_f32 v5, v14, v15
	global_store_dwordx4 v[18:19], v[8:11], off
	global_store_dwordx4 v[18:19], v[2:5], off offset:256
	s_and_saveexec_b64 s[34:35], s[4:5]
	s_cbranch_execz .LBB0_718
	v_lshlrev_b64 v[2:3], 7, v[16:17]
	v_lshl_add_u64 v[2:3], s[0:1], 0, v[2:3]
	v_lshl_add_u64 v[2:3], s[30:31], 2, v[2:3]
	s_lshl_b32 s10, s46, 2
	v_lshl_add_u64 v[2:3], v[2:3], 0, s[10:11]
	s_waitcnt lgkmcnt(0)
	v_add_f32_e32 v0, v0, v1
	global_store_dword v[2:3], v0, off

; #define LAS __attribute__((address_space(3)))
; DI float dot4(const f32x4 a) { return (a[0] * a[0] + a[1] * a[1]) + (a[2] * a[2] + a[3] * a[3]); }
;     DI void fused(f32x4 (&acc)[2][2][4][2], const Unit& u, int wr, int wc, int fr, int fq, LAS unsigned char* lds, int wid, int lane) const {
;         LAS float* P = (LAS float*)lds;
;         LAS float* R = (LAS float*)(lds + 4096);
;         const int col0 = u.pn * 256 + wc * 32 + 8 * fq;
; #pragma unroll
;         for (int ai = 0; ai < 2; ++ai)
; #pragma unroll
;             for (int m = 0; m < 4; ++m) {
;                 const int rl = ai * 128 + wr * 64 + m * 16 + fr;
;                 const size_t off = (size_t)(u.pm * 256 + rl) * DM + col0;
;                 float ss = 0.f;
; #pragma unroll
;                 for (int bj = 0; bj < 2; ++bj) {
;                     const u32x4 w = *(const u32x4*)(xb + off + bj * 128);
;                     acc[ai][bj][m][0] += (f32x4){bflo(w.x), bfhi(w.x), bflo(w.y), bfhi(w.y)};
;                     acc[ai][bj][m][1] += (f32x4){bflo(w.z), bfhi(w.z), bflo(w.w), bfhi(w.w)};
;                     ss += dot4(acc[ai][bj][m][0]) + dot4(acc[ai][bj][m][1]);
;                 }
;                 ss += __shfl_xor(ss, 16); ss += __shfl_xor(ss, 32);
;                 if (fq == 0) P[rl * 4 + wc] = ss;
;             }
.LBB0_1230:
	s_lshl_b32 s3, s9, 5
	s_lshl_b32 s4, s10, 8
	s_or_b32 s3, s4, s3
	v_and_or_b32 v128, v148, 24, s3
	s_lshl_b32 s3, s8, 8
	v_add_u32_e32 v130, s3, v162
	v_ashrrev_i32_e32 v131, 31, v130
	v_lshlrev_b64 v[132:133], 12, v[130:131]
	v_ashrrev_i32_e32 v129, 31, v128
	v_lshl_add_u64 v[132:133], s[62:63], 0, v[132:133]
	v_lshl_add_u64 v[136:137], v[128:129], 1, v[132:133]
	s_waitcnt vmcnt(0)
	s_barrier
	global_load_dwordx4 v[132:135], v[136:137], off
	s_nop 0
	global_load_dwordx4 v[136:139], v[136:137], off offset:256
	v_mbcnt_lo_u32_b32 v140, -1, 0
	v_mbcnt_hi_u32_b32 v148, -1, v140
	v_and_b32_e32 v141, 64, v148
	v_xor_b32_e32 v140, 16, v148
	v_add_u32_e32 v149, 64, v141
	v_cmp_lt_i32_e32 vcc, v140, v149
	s_lshl_b32 s4, s9, 2
	s_add_i32 s6, s4, 0
	v_cndmask_b32_e32 v140, v148, v140, vcc
	v_lshlrev_b32_e32 v163, 2, v140
	s_waitcnt vmcnt(0)
	v_lshlrev_b32_e32 v140, 16, v132
	v_and_b32_e32 v141, 0xffff0000, v132
	v_lshlrev_b32_e32 v132, 16, v133
	v_and_b32_e32 v133, 0xffff0000, v133
	v_lshlrev_b32_e32 v142, 16, v134
	v_and_b32_e32 v143, 0xffff0000, v134
	v_lshlrev_b32_e32 v134, 16, v135
	v_and_b32_e32 v135, 0xffff0000, v135
	v_lshlrev_b32_e32 v144, 16, v136
	v_and_b32_e32 v145, 0xffff0000, v136
	v_lshlrev_b32_e32 v136, 16, v137
	v_and_b32_e32 v137, 0xffff0000, v137
	v_lshlrev_b32_e32 v146, 16, v138
	v_and_b32_e32 v147, 0xffff0000, v138
	v_lshlrev_b32_e32 v138, 16, v139
	v_and_b32_e32 v139, 0xffff0000, v139
	v_pk_add_f32 v[126:127], v[126:127], v[132:133]
	v_pk_add_f32 v[124:125], v[124:125], v[140:141]
	v_pk_add_f32 v[122:123], v[122:123], v[134:135]
	v_pk_add_f32 v[120:121], v[120:121], v[142:143]
	v_pk_add_f32 v[118:119], v[118:119], v[136:137]
	v_pk_add_f32 v[116:117], v[116:117], v[144:145]
	v_pk_add_f32 v[114:115], v[114:115], v[138:139]
	v_pk_add_f32 v[112:113], v[112:113], v[146:147]
	v_mul_f32_e32 v132, v125, v125
	v_mul_f32_e32 v133, v127, v127
	v_mul_f32_e32 v134, v121, v121
	v_mul_f32_e32 v135, v123, v123
	v_mul_f32_e32 v136, v117, v117
	v_mul_f32_e32 v137, v119, v119
	v_mul_f32_e32 v138, v113, v113
	v_mul_f32_e32 v139, v115, v115
	v_fmac_f32_e32 v132, v124, v124
	v_fmac_f32_e32 v133, v126, v126
	v_fmac_f32_e32 v134, v120, v120
	v_fmac_f32_e32 v135, v122, v122
	v_fmac_f32_e32 v136, v116, v116
	v_fmac_f32_e32 v137, v118, v118
	v_fmac_f32_e32 v138, v112, v112
	v_fmac_f32_e32 v139, v114, v114
	v_add_f32_e32 v132, v132, v133
	v_add_f32_e32 v133, v134, v135
	v_add_f32_e32 v134, v136, v137
	v_add_f32_e32 v135, v138, v139
	v_add_f32_e32 v132, v132, v133
	v_add_f32_e32 v133, v134, v135
	v_add_f32_e32 v132, v132, v133
	v_mov_b32_e32 v133, v132
	s_nop 1
	v_permlane16_swap_b32_e32 v133, v132
	v_xor_b32_e32 v134, 32, v148
	v_cmp_lt_i32_e32 vcc, v134, v149
	s_waitcnt lgkmcnt(0)
	v_add_f32_e32 v132, v132, v133
	v_cndmask_b32_e32 v134, v148, v134, vcc
	v_lshlrev_b32_e32 v164, 2, v134
	v_mov_b32_e32 v133, v132
	s_nop 1
	v_permlane32_swap_b32_e32 v133, v132
	v_cmp_gt_u32_e32 vcc, 16, v252
	s_and_saveexec_b64 s[4:5], vcc
	s_cbranch_execz .LBB0_1232
	v_lshl_add_u32 v134, v162, 4, s6
	s_waitcnt lgkmcnt(0)
	v_add_f32_e32 v132, v132, v133
	ds_write_b32 v134, v132
.LBB0_1232:
	s_or_b64 exec, exec, s[4:5]
	v_or_b32_e32 v134, 16, v162
	v_add_u32_e32 v132, s3, v134
	s_waitcnt lgkmcnt(0)
	v_ashrrev_i32_e32 v133, 31, v132
	v_lshlrev_b64 v[136:137], 12, v[132:133]
	v_lshl_add_u64 v[136:137], s[62:63], 0, v[136:137]
	v_lshl_add_u64 v[140:141], v[128:129], 1, v[136:137]
	global_load_dwordx4 v[136:139], v[140:141], off
	s_nop 0
	global_load_dwordx4 v[140:143], v[140:141], off offset:256
	s_waitcnt vmcnt(1)
	v_lshlrev_b32_e32 v144, 16, v136
	v_and_b32_e32 v145, 0xffff0000, v136
	v_lshlrev_b32_e32 v136, 16, v137
	v_and_b32_e32 v137, 0xffff0000, v137
	v_lshlrev_b32_e32 v146, 16, v138
	v_and_b32_e32 v147, 0xffff0000, v138
	v_lshlrev_b32_e32 v138, 16, v139
	v_and_b32_e32 v139, 0xffff0000, v139
	s_waitcnt vmcnt(0)
	v_lshlrev_b32_e32 v148, 16, v140
	v_and_b32_e32 v149, 0xffff0000, v140
	v_lshlrev_b32_e32 v140, 16, v141
	v_and_b32_e32 v141, 0xffff0000, v141
	v_lshlrev_b32_e32 v150, 16, v142
	v_and_b32_e32 v151, 0xffff0000, v142
	v_lshlrev_b32_e32 v142, 16, v143
	v_and_b32_e32 v143, 0xffff0000, v143
	v_pk_add_f32 v[110:111], v[110:111], v[136:137]
	v_pk_add_f32 v[108:109], v[108:109], v[144:145]
	v_pk_add_f32 v[106:107], v[106:107], v[138:139]
	v_pk_add_f32 v[104:105], v[104:105], v[146:147]
	v_pk_add_f32 v[102:103], v[102:103], v[140:141]
	v_pk_add_f32 v[100:101], v[100:101], v[148:149]
	v_pk_add_f32 v[98:99], v[98:99], v[142:143]
	v_pk_add_f32 v[96:97], v[96:97], v[150:151]
	v_mul_f32_e32 v135, v109, v109
	v_mul_f32_e32 v136, v111, v111
	v_mul_f32_e32 v137, v105, v105
	v_mul_f32_e32 v138, v107, v107
	v_mul_f32_e32 v139, v101, v101
	v_mul_f32_e32 v140, v103, v103
	v_mul_f32_e32 v141, v97, v97
	v_mul_f32_e32 v142, v99, v99
	v_fmac_f32_e32 v135, v108, v108
	v_fmac_f32_e32 v136, v110, v110
	v_fmac_f32_e32 v137, v104, v104
	v_fmac_f32_e32 v138, v106, v106
	v_fmac_f32_e32 v139, v100, v100
	v_fmac_f32_e32 v140, v102, v102
	v_fmac_f32_e32 v141, v96, v96
	v_fmac_f32_e32 v142, v98, v98
	v_add_f32_e32 v135, v135, v136
	v_add_f32_e32 v136, v137, v138
	v_add_f32_e32 v137, v139, v140
	v_add_f32_e32 v138, v141, v142
	v_add_f32_e32 v135, v135, v136
	v_add_f32_e32 v136, v137, v138
	v_add_f32_e32 v135, v135, v136
	v_mov_b32_e32 v136, v135
	s_nop 1
	v_permlane16_swap_b32_e32 v136, v135
	s_waitcnt lgkmcnt(0)
	v_add_f32_e32 v135, v135, v136
	v_mov_b32_e32 v136, v135
	s_nop 1
	v_permlane32_swap_b32_e32 v136, v135
	s_and_saveexec_b64 s[4:5], vcc
	s_cbranch_execz .LBB0_1234
	v_lshl_add_u32 v134, v134, 4, s6
	s_waitcnt lgkmcnt(0)
	v_add_f32_e32 v135, v135, v136
	ds_write_b32 v134, v135
; DI float dot4(const f32x4 a) { return (a[0] * a[0] + a[1] * a[1]) + (a[2] * a[2] + a[3] * a[3]); }
;     DI void fused(f32x4 (&acc)[2][2][4][2], const Unit& u, int wr, int wc, int fr, int fq, LAS unsigned char* lds, int wid, int lane) const {
;     ...
;         for (int ai = 0; ai < 2; ++ai)
; #pragma unroll
;             for (int m = 0; m < 4; ++m) {
;                 const int rl = ai * 128 + wr * 64 + m * 16 + fr;
;                 const size_t off = (size_t)(u.pm * 256 + rl) * DM + col0;
;                 float ss = 0.f;
; #pragma unroll
;                 for (int bj = 0; bj < 2; ++bj) {
;                     const u32x4 w = *(const u32x4*)(xb + off + bj * 128);
;                     acc[ai][bj][m][0] += (f32x4){bflo(w.x), bfhi(w.x), bflo(w.y), bfhi(w.y)};
;                     acc[ai][bj][m][1] += (f32x4){bflo(w.z), bfhi(w.z), bflo(w.w), bfhi(w.w)};
;                     ss += dot4(acc[ai][bj][m][0]) + dot4(acc[ai][bj][m][1]);
;                 }
;                 ss += __shfl_xor(ss, 16); ss += __shfl_xor(ss, 32);
;                 if (fq == 0) P[rl * 4 + wc] = ss;
;             }
.LBB0_1234:
	s_or_b64 exec, exec, s[4:5]
	s_waitcnt lgkmcnt(0)
	v_or_b32_e32 v136, 32, v162
	v_add_u32_e32 v134, s3, v136
	v_ashrrev_i32_e32 v135, 31, v134
	v_lshlrev_b64 v[138:139], 12, v[134:135]
	v_lshl_add_u64 v[138:139], s[62:63], 0, v[138:139]
	v_lshl_add_u64 v[142:143], v[128:129], 1, v[138:139]
	global_load_dwordx4 v[138:141], v[142:143], off
	s_nop 0
	global_load_dwordx4 v[142:145], v[142:143], off offset:256
	s_waitcnt vmcnt(1)
	v_lshlrev_b32_e32 v146, 16, v138
	v_and_b32_e32 v147, 0xffff0000, v138
	v_lshlrev_b32_e32 v138, 16, v139
	v_and_b32_e32 v139, 0xffff0000, v139
	v_lshlrev_b32_e32 v148, 16, v140
	v_and_b32_e32 v149, 0xffff0000, v140
	v_lshlrev_b32_e32 v140, 16, v141
	v_and_b32_e32 v141, 0xffff0000, v141
	s_waitcnt vmcnt(0)
	v_lshlrev_b32_e32 v150, 16, v142
	v_and_b32_e32 v151, 0xffff0000, v142
	v_lshlrev_b32_e32 v142, 16, v143
	v_and_b32_e32 v143, 0xffff0000, v143
	v_lshlrev_b32_e32 v152, 16, v144
	v_and_b32_e32 v153, 0xffff0000, v144
	v_lshlrev_b32_e32 v144, 16, v145
	v_and_b32_e32 v145, 0xffff0000, v145
	v_pk_add_f32 v[94:95], v[94:95], v[138:139]
	v_pk_add_f32 v[92:93], v[92:93], v[146:147]
	v_pk_add_f32 v[90:91], v[90:91], v[140:141]
	v_pk_add_f32 v[88:89], v[88:89], v[148:149]
	v_pk_add_f32 v[86:87], v[86:87], v[142:143]
	v_pk_add_f32 v[84:85], v[84:85], v[150:151]
	v_pk_add_f32 v[82:83], v[82:83], v[144:145]
	v_pk_add_f32 v[80:81], v[80:81], v[152:153]
	v_mul_f32_e32 v137, v93, v93
	v_mul_f32_e32 v138, v95, v95
	v_mul_f32_e32 v139, v89, v89
	v_mul_f32_e32 v140, v91, v91
	v_mul_f32_e32 v141, v85, v85
	v_mul_f32_e32 v142, v87, v87
	v_mul_f32_e32 v143, v81, v81
	v_mul_f32_e32 v144, v83, v83
	v_fmac_f32_e32 v137, v92, v92
	v_fmac_f32_e32 v138, v94, v94
	v_fmac_f32_e32 v139, v88, v88
	v_fmac_f32_e32 v140, v90, v90
	v_fmac_f32_e32 v141, v84, v84
	v_fmac_f32_e32 v142, v86, v86
	v_fmac_f32_e32 v143, v80, v80
	v_fmac_f32_e32 v144, v82, v82
	v_add_f32_e32 v137, v137, v138
	v_add_f32_e32 v138, v139, v140
	v_add_f32_e32 v139, v141, v142
	v_add_f32_e32 v140, v143, v144
	v_add_f32_e32 v137, v137, v138
	v_add_f32_e32 v138, v139, v140
	v_add_f32_e32 v137, v137, v138
	v_mov_b32_e32 v138, v137
	s_nop 1
	v_permlane16_swap_b32_e32 v138, v137
	s_waitcnt lgkmcnt(0)
	v_add_f32_e32 v137, v137, v138
	v_mov_b32_e32 v138, v137
	s_nop 1
	v_permlane32_swap_b32_e32 v138, v137
	s_and_saveexec_b64 s[4:5], vcc
	s_cbranch_execz .LBB0_1236
	v_lshl_add_u32 v136, v136, 4, s6
	s_waitcnt lgkmcnt(0)
	v_add_f32_e32 v137, v137, v138
	ds_write_b32 v136, v137
.LBB0_1236:
	s_or_b64 exec, exec, s[4:5]
	s_waitcnt lgkmcnt(0)
	v_or_b32_e32 v138, 48, v162
	v_add_u32_e32 v136, s3, v138
	v_ashrrev_i32_e32 v137, 31, v136
	v_lshlrev_b64 v[140:141], 12, v[136:137]
	v_lshl_add_u64 v[140:141], s[62:63], 0, v[140:141]
	v_lshl_add_u64 v[144:145], v[128:129], 1, v[140:141]
	global_load_dwordx4 v[140:143], v[144:145], off
	s_nop 0
	global_load_dwordx4 v[144:147], v[144:145], off offset:256
	s_waitcnt vmcnt(1)
	v_lshlrev_b32_e32 v148, 16, v140
	v_and_b32_e32 v149, 0xffff0000, v140
	v_lshlrev_b32_e32 v140, 16, v141
	v_and_b32_e32 v141, 0xffff0000, v141
	v_lshlrev_b32_e32 v150, 16, v142
	v_and_b32_e32 v151, 0xffff0000, v142
	v_lshlrev_b32_e32 v142, 16, v143
	v_and_b32_e32 v143, 0xffff0000, v143
	s_waitcnt vmcnt(0)
	v_lshlrev_b32_e32 v152, 16, v144
	v_and_b32_e32 v153, 0xffff0000, v144
	v_lshlrev_b32_e32 v144, 16, v145
	v_and_b32_e32 v145, 0xffff0000, v145
	v_lshlrev_b32_e32 v154, 16, v146
	v_and_b32_e32 v155, 0xffff0000, v146
	v_lshlrev_b32_e32 v146, 16, v147
	v_and_b32_e32 v147, 0xffff0000, v147
	v_pk_add_f32 v[78:79], v[78:79], v[140:141]
	v_pk_add_f32 v[76:77], v[76:77], v[148:149]
	v_pk_add_f32 v[74:75], v[74:75], v[142:143]
	v_pk_add_f32 v[72:73], v[72:73], v[150:151]
	v_pk_add_f32 v[70:71], v[70:71], v[144:145]
	v_pk_add_f32 v[68:69], v[68:69], v[152:153]
	v_pk_add_f32 v[66:67], v[66:67], v[146:147]
	v_pk_add_f32 v[64:65], v[64:65], v[154:155]
	v_mul_f32_e32 v139, v77, v77
	v_mul_f32_e32 v140, v79, v79
	v_mul_f32_e32 v141, v73, v73
	v_mul_f32_e32 v142, v75, v75
	v_mul_f32_e32 v143, v69, v69
	v_mul_f32_e32 v144, v71, v71
	v_mul_f32_e32 v145, v65, v65
	v_mul_f32_e32 v146, v67, v67
	v_fmac_f32_e32 v139, v76, v76
	v_fmac_f32_e32 v140, v78, v78
	v_fmac_f32_e32 v141, v72, v72
	v_fmac_f32_e32 v142, v74, v74
	v_fmac_f32_e32 v143, v68, v68
	v_fmac_f32_e32 v144, v70, v70
	v_fmac_f32_e32 v145, v64, v64
	v_fmac_f32_e32 v146, v66, v66
	v_add_f32_e32 v139, v139, v140
	v_add_f32_e32 v140, v141, v142
	v_add_f32_e32 v141, v143, v144
	v_add_f32_e32 v142, v145, v146
	v_add_f32_e32 v139, v139, v140
	v_add_f32_e32 v140, v141, v142
	v_add_f32_e32 v139, v139, v140
	v_mov_b32_e32 v140, v139
	s_nop 1
	v_permlane16_swap_b32_e32 v140, v139
	s_waitcnt lgkmcnt(0)
	v_add_f32_e32 v139, v139, v140
	v_mov_b32_e32 v140, v139
	s_nop 1
	v_permlane32_swap_b32_e32 v140, v139
	s_and_saveexec_b64 s[4:5], vcc
	s_cbranch_execz .LBB0_1238
	v_lshl_add_u32 v138, v138, 4, s6
	s_waitcnt lgkmcnt(0)
	v_add_f32_e32 v139, v139, v140
	ds_write_b32 v138, v139
; DI float dot4(const f32x4 a) { return (a[0] * a[0] + a[1] * a[1]) + (a[2] * a[2] + a[3] * a[3]); }
;     DI void fused(f32x4 (&acc)[2][2][4][2], const Unit& u, int wr, int wc, int fr, int fq, LAS unsigned char* lds, int wid, int lane) const {
;     ...
;         for (int ai = 0; ai < 2; ++ai)
; #pragma unroll
;             for (int m = 0; m < 4; ++m) {
;                 const int rl = ai * 128 + wr * 64 + m * 16 + fr;
;                 const size_t off = (size_t)(u.pm * 256 + rl) * DM + col0;
;                 float ss = 0.f;
; #pragma unroll
;                 for (int bj = 0; bj < 2; ++bj) {
;                     const u32x4 w = *(const u32x4*)(xb + off + bj * 128);
;                     acc[ai][bj][m][0] += (f32x4){bflo(w.x), bfhi(w.x), bflo(w.y), bfhi(w.y)};
;                     acc[ai][bj][m][1] += (f32x4){bflo(w.z), bfhi(w.z), bflo(w.w), bfhi(w.w)};
;                     ss += dot4(acc[ai][bj][m][0]) + dot4(acc[ai][bj][m][1]);
;                 }
;                 ss += __shfl_xor(ss, 16); ss += __shfl_xor(ss, 32);
;                 if (fq == 0) P[rl * 4 + wc] = ss;
;             }
.LBB0_1238:
	s_or_b64 exec, exec, s[4:5]
	s_waitcnt lgkmcnt(0)
	v_add_u32_e32 v140, 0x80, v162
	v_add_u32_e32 v138, s3, v140
	v_ashrrev_i32_e32 v139, 31, v138
	v_lshlrev_b64 v[142:143], 12, v[138:139]
	v_lshl_add_u64 v[142:143], s[62:63], 0, v[142:143]
	v_lshl_add_u64 v[146:147], v[128:129], 1, v[142:143]
	global_load_dwordx4 v[142:145], v[146:147], off
	s_nop 0
	global_load_dwordx4 v[146:149], v[146:147], off offset:256
	s_waitcnt vmcnt(1)
	v_lshlrev_b32_e32 v150, 16, v142
	v_and_b32_e32 v151, 0xffff0000, v142
	v_lshlrev_b32_e32 v142, 16, v143
	v_and_b32_e32 v143, 0xffff0000, v143
	v_lshlrev_b32_e32 v152, 16, v144
	v_and_b32_e32 v153, 0xffff0000, v144
	v_lshlrev_b32_e32 v144, 16, v145
	v_and_b32_e32 v145, 0xffff0000, v145
	s_waitcnt vmcnt(0)
	v_lshlrev_b32_e32 v154, 16, v146
	v_and_b32_e32 v155, 0xffff0000, v146
	v_lshlrev_b32_e32 v146, 16, v147
	v_and_b32_e32 v147, 0xffff0000, v147
	v_lshlrev_b32_e32 v156, 16, v148
	v_and_b32_e32 v157, 0xffff0000, v148
	v_lshlrev_b32_e32 v148, 16, v149
	v_and_b32_e32 v149, 0xffff0000, v149
	v_pk_add_f32 v[62:63], v[62:63], v[142:143]
	v_pk_add_f32 v[60:61], v[60:61], v[150:151]
	v_pk_add_f32 v[58:59], v[58:59], v[144:145]
	v_pk_add_f32 v[56:57], v[56:57], v[152:153]
	v_pk_add_f32 v[54:55], v[54:55], v[146:147]
	v_pk_add_f32 v[52:53], v[52:53], v[154:155]
	v_pk_add_f32 v[50:51], v[50:51], v[148:149]
	v_pk_add_f32 v[48:49], v[48:49], v[156:157]
	v_mul_f32_e32 v141, v61, v61
	v_mul_f32_e32 v142, v63, v63
	v_mul_f32_e32 v143, v57, v57
	v_mul_f32_e32 v144, v59, v59
	v_mul_f32_e32 v145, v53, v53
	v_mul_f32_e32 v146, v55, v55
	v_mul_f32_e32 v147, v49, v49
	v_mul_f32_e32 v148, v51, v51
	v_fmac_f32_e32 v141, v60, v60
	v_fmac_f32_e32 v142, v62, v62
	v_fmac_f32_e32 v143, v56, v56
	v_fmac_f32_e32 v144, v58, v58
	v_fmac_f32_e32 v145, v52, v52
	v_fmac_f32_e32 v146, v54, v54
	v_fmac_f32_e32 v147, v48, v48
	v_fmac_f32_e32 v148, v50, v50
	v_add_f32_e32 v141, v141, v142
	v_add_f32_e32 v142, v143, v144
	v_add_f32_e32 v143, v145, v146
	v_add_f32_e32 v144, v147, v148
	v_add_f32_e32 v141, v141, v142
	v_add_f32_e32 v142, v143, v144
	v_add_f32_e32 v141, v141, v142
	v_mov_b32_e32 v142, v141
	s_nop 1
	v_permlane16_swap_b32_e32 v142, v141
	s_waitcnt lgkmcnt(0)
	v_add_f32_e32 v141, v141, v142
	v_mov_b32_e32 v142, v141
	s_nop 1
	v_permlane32_swap_b32_e32 v142, v141
	s_and_saveexec_b64 s[4:5], vcc
	s_cbranch_execz .LBB0_1240
	v_lshl_add_u32 v140, v140, 4, s6
	s_waitcnt lgkmcnt(0)
	v_add_f32_e32 v141, v141, v142
	ds_write_b32 v140, v141
.LBB0_1240:
	s_or_b64 exec, exec, s[4:5]
	s_waitcnt lgkmcnt(0)
	v_add_u32_e32 v142, 0x90, v162
	v_add_u32_e32 v140, s3, v142
	v_ashrrev_i32_e32 v141, 31, v140
	v_lshlrev_b64 v[144:145], 12, v[140:141]
	v_lshl_add_u64 v[144:145], s[62:63], 0, v[144:145]
	v_lshl_add_u64 v[148:149], v[128:129], 1, v[144:145]
	global_load_dwordx4 v[144:147], v[148:149], off
	s_nop 0
	global_load_dwordx4 v[148:151], v[148:149], off offset:256
	s_waitcnt vmcnt(1)
	v_lshlrev_b32_e32 v152, 16, v144
	v_and_b32_e32 v153, 0xffff0000, v144
	v_lshlrev_b32_e32 v144, 16, v145
	v_and_b32_e32 v145, 0xffff0000, v145
	v_lshlrev_b32_e32 v154, 16, v146
	v_and_b32_e32 v155, 0xffff0000, v146
	v_lshlrev_b32_e32 v146, 16, v147
	v_and_b32_e32 v147, 0xffff0000, v147
	s_waitcnt vmcnt(0)
	v_lshlrev_b32_e32 v156, 16, v148
	v_and_b32_e32 v157, 0xffff0000, v148
	v_lshlrev_b32_e32 v148, 16, v149
	v_and_b32_e32 v149, 0xffff0000, v149
	v_lshlrev_b32_e32 v158, 16, v150
	v_and_b32_e32 v159, 0xffff0000, v150
	v_lshlrev_b32_e32 v150, 16, v151
	v_and_b32_e32 v151, 0xffff0000, v151
	v_pk_add_f32 v[46:47], v[46:47], v[144:145]
	v_pk_add_f32 v[44:45], v[44:45], v[152:153]
	v_pk_add_f32 v[42:43], v[42:43], v[146:147]
	v_pk_add_f32 v[40:41], v[40:41], v[154:155]
	v_pk_add_f32 v[38:39], v[38:39], v[148:149]
	v_pk_add_f32 v[36:37], v[36:37], v[156:157]
	v_pk_add_f32 v[34:35], v[34:35], v[150:151]
	v_pk_add_f32 v[32:33], v[32:33], v[158:159]
	v_mul_f32_e32 v143, v45, v45
	v_mul_f32_e32 v144, v47, v47
	v_mul_f32_e32 v145, v41, v41
	v_mul_f32_e32 v146, v43, v43
	v_mul_f32_e32 v147, v37, v37
	v_mul_f32_e32 v148, v39, v39
	v_mul_f32_e32 v149, v33, v33
	v_mul_f32_e32 v150, v35, v35
	v_fmac_f32_e32 v143, v44, v44
	v_fmac_f32_e32 v144, v46, v46
	v_fmac_f32_e32 v145, v40, v40
	v_fmac_f32_e32 v146, v42, v42
	v_fmac_f32_e32 v147, v36, v36
	v_fmac_f32_e32 v148, v38, v38
	v_fmac_f32_e32 v149, v32, v32
	v_fmac_f32_e32 v150, v34, v34
	v_add_f32_e32 v143, v143, v144
	v_add_f32_e32 v144, v145, v146
	v_add_f32_e32 v145, v147, v148
	v_add_f32_e32 v146, v149, v150
	v_add_f32_e32 v143, v143, v144
	v_add_f32_e32 v144, v145, v146
	v_add_f32_e32 v143, v143, v144
	v_mov_b32_e32 v144, v143
	s_nop 1
	v_permlane16_swap_b32_e32 v144, v143
	s_waitcnt lgkmcnt(0)
	v_add_f32_e32 v143, v143, v144
	v_mov_b32_e32 v144, v143
	s_nop 1
	v_permlane32_swap_b32_e32 v144, v143
	s_and_saveexec_b64 s[4:5], vcc
	s_cbranch_execz .LBB0_1242
	v_lshl_add_u32 v142, v142, 4, s6
	s_waitcnt lgkmcnt(0)
	v_add_f32_e32 v143, v143, v144
	ds_write_b32 v142, v143
; DI float dot4(const f32x4 a) { return (a[0] * a[0] + a[1] * a[1]) + (a[2] * a[2] + a[3] * a[3]); }
;     DI void fused(f32x4 (&acc)[2][2][4][2], const Unit& u, int wr, int wc, int fr, int fq, LAS unsigned char* lds, int wid, int lane) const {
;     ...
;         for (int ai = 0; ai < 2; ++ai)
; #pragma unroll
;             for (int m = 0; m < 4; ++m) {
;                 const int rl = ai * 128 + wr * 64 + m * 16 + fr;
;                 const size_t off = (size_t)(u.pm * 256 + rl) * DM + col0;
;                 float ss = 0.f;
; #pragma unroll
;                 for (int bj = 0; bj < 2; ++bj) {
;                     const u32x4 w = *(const u32x4*)(xb + off + bj * 128);
;                     acc[ai][bj][m][0] += (f32x4){bflo(w.x), bfhi(w.x), bflo(w.y), bfhi(w.y)};
;                     acc[ai][bj][m][1] += (f32x4){bflo(w.z), bfhi(w.z), bflo(w.w), bfhi(w.w)};
;                     ss += dot4(acc[ai][bj][m][0]) + dot4(acc[ai][bj][m][1]);
;                 }
;                 ss += __shfl_xor(ss, 16); ss += __shfl_xor(ss, 32);
;                 if (fq == 0) P[rl * 4 + wc] = ss;
;             }
.LBB0_1242:
	s_or_b64 exec, exec, s[4:5]
	s_waitcnt lgkmcnt(0)
	v_add_u32_e32 v144, 0xa0, v162
	v_add_u32_e32 v142, s3, v144
	v_ashrrev_i32_e32 v143, 31, v142
	v_lshlrev_b64 v[146:147], 12, v[142:143]
	v_lshl_add_u64 v[146:147], s[62:63], 0, v[146:147]
	v_lshl_add_u64 v[150:151], v[128:129], 1, v[146:147]
	global_load_dwordx4 v[146:149], v[150:151], off
	s_nop 0
	global_load_dwordx4 v[150:153], v[150:151], off offset:256
	s_waitcnt vmcnt(1)
	v_lshlrev_b32_e32 v154, 16, v146
	v_and_b32_e32 v155, 0xffff0000, v146
	v_lshlrev_b32_e32 v146, 16, v147
	v_and_b32_e32 v147, 0xffff0000, v147
	v_lshlrev_b32_e32 v156, 16, v148
	v_and_b32_e32 v157, 0xffff0000, v148
	v_lshlrev_b32_e32 v148, 16, v149
	v_and_b32_e32 v149, 0xffff0000, v149
	s_waitcnt vmcnt(0)
	v_lshlrev_b32_e32 v158, 16, v150
	v_and_b32_e32 v159, 0xffff0000, v150
	v_lshlrev_b32_e32 v150, 16, v151
	v_and_b32_e32 v151, 0xffff0000, v151
	v_lshlrev_b32_e32 v160, 16, v152
	v_and_b32_e32 v161, 0xffff0000, v152
	v_lshlrev_b32_e32 v152, 16, v153
	v_and_b32_e32 v153, 0xffff0000, v153
	v_pk_add_f32 v[30:31], v[30:31], v[146:147]
	v_pk_add_f32 v[28:29], v[28:29], v[154:155]
	v_pk_add_f32 v[26:27], v[26:27], v[148:149]
	v_pk_add_f32 v[24:25], v[24:25], v[156:157]
	v_pk_add_f32 v[22:23], v[22:23], v[150:151]
	v_pk_add_f32 v[20:21], v[20:21], v[158:159]
	v_pk_add_f32 v[18:19], v[18:19], v[152:153]
	v_pk_add_f32 v[16:17], v[16:17], v[160:161]
	v_mul_f32_e32 v145, v29, v29
	v_mul_f32_e32 v146, v31, v31
	v_mul_f32_e32 v147, v25, v25
	v_mul_f32_e32 v148, v27, v27
	v_mul_f32_e32 v149, v21, v21
	v_mul_f32_e32 v150, v23, v23
	v_mul_f32_e32 v151, v17, v17
	v_mul_f32_e32 v152, v19, v19
	v_fmac_f32_e32 v145, v28, v28
	v_fmac_f32_e32 v146, v30, v30
	v_fmac_f32_e32 v147, v24, v24
	v_fmac_f32_e32 v148, v26, v26
	v_fmac_f32_e32 v149, v20, v20
	v_fmac_f32_e32 v150, v22, v22
	v_fmac_f32_e32 v151, v16, v16
	v_fmac_f32_e32 v152, v18, v18
	v_add_f32_e32 v145, v145, v146
	v_add_f32_e32 v146, v147, v148
	v_add_f32_e32 v147, v149, v150
	v_add_f32_e32 v148, v151, v152
	v_add_f32_e32 v145, v145, v146
	v_add_f32_e32 v146, v147, v148
	v_add_f32_e32 v145, v145, v146
	v_mov_b32_e32 v146, v145
	s_nop 1
	v_permlane16_swap_b32_e32 v146, v145
	s_waitcnt lgkmcnt(0)
	v_add_f32_e32 v145, v145, v146
	v_mov_b32_e32 v146, v145
	s_nop 1
	v_permlane32_swap_b32_e32 v146, v145
	s_and_saveexec_b64 s[4:5], vcc
	s_cbranch_execz .LBB0_1244
	v_lshl_add_u32 v144, v144, 4, s6
	s_waitcnt lgkmcnt(0)
	v_add_f32_e32 v145, v145, v146
	ds_write_b32 v144, v145
.LBB0_1244:
	s_or_b64 exec, exec, s[4:5]
	v_add_u32_e32 v165, 0xb0, v162
	v_add_u32_e32 v144, s3, v165
	v_ashrrev_i32_e32 v145, 31, v144
	s_waitcnt lgkmcnt(0)
	v_lshlrev_b64 v[146:147], 12, v[144:145]
	v_lshl_add_u64 v[146:147], s[62:63], 0, v[146:147]
	v_lshl_add_u64 v[150:151], v[128:129], 1, v[146:147]
	global_load_dwordx4 v[146:149], v[150:151], off
	s_nop 0
	global_load_dwordx4 v[150:153], v[150:151], off offset:256
	s_waitcnt vmcnt(1)
	v_lshlrev_b32_e32 v154, 16, v146
	v_and_b32_e32 v155, 0xffff0000, v146
	v_lshlrev_b32_e32 v146, 16, v147
	v_and_b32_e32 v147, 0xffff0000, v147
	v_lshlrev_b32_e32 v156, 16, v148
	v_and_b32_e32 v157, 0xffff0000, v148
	v_lshlrev_b32_e32 v148, 16, v149
	v_and_b32_e32 v149, 0xffff0000, v149
	s_waitcnt vmcnt(0)
	v_lshlrev_b32_e32 v166, 16, v150
	v_and_b32_e32 v167, 0xffff0000, v150
	v_lshlrev_b32_e32 v150, 16, v151
	v_and_b32_e32 v151, 0xffff0000, v151
	v_lshlrev_b32_e32 v168, 16, v152
	v_and_b32_e32 v169, 0xffff0000, v152
	v_lshlrev_b32_e32 v170, 16, v153
	v_and_b32_e32 v171, 0xffff0000, v153
	v_pk_add_f32 v[158:159], v[14:15], v[146:147]
	v_pk_add_f32 v[160:161], v[12:13], v[154:155]
	v_pk_add_f32 v[154:155], v[10:11], v[148:149]
	v_pk_add_f32 v[156:157], v[8:9], v[156:157]
	v_pk_add_f32 v[148:149], v[6:7], v[150:151]
	v_pk_add_f32 v[152:153], v[4:5], v[166:167]
	v_pk_add_f32 v[146:147], v[2:3], v[170:171]
	v_pk_add_f32 v[150:151], v[0:1], v[168:169]
	v_mul_f32_e32 v0, v161, v161
	v_mul_f32_e32 v1, v159, v159
	v_mul_f32_e32 v2, v157, v157
	v_mul_f32_e32 v3, v155, v155
	v_mul_f32_e32 v4, v153, v153
	v_mul_f32_e32 v5, v149, v149
	v_mul_f32_e32 v6, v151, v151
	v_mul_f32_e32 v7, v147, v147
	v_fmac_f32_e32 v0, v160, v160
	v_fmac_f32_e32 v1, v158, v158
	v_fmac_f32_e32 v2, v156, v156
	v_fmac_f32_e32 v3, v154, v154
	v_fmac_f32_e32 v4, v152, v152
	v_fmac_f32_e32 v5, v148, v148
	v_fmac_f32_e32 v6, v150, v150
	v_fmac_f32_e32 v7, v146, v146
	v_add_f32_e32 v0, v0, v1
	v_add_f32_e32 v1, v2, v3
	v_add_f32_e32 v2, v4, v5
	v_add_f32_e32 v3, v6, v7
	v_add_f32_e32 v0, v0, v1
	v_add_f32_e32 v1, v2, v3
	v_add_f32_e32 v0, v0, v1
	v_mov_b32_e32 v1, v0
	s_nop 1
	v_permlane16_swap_b32_e32 v1, v0
	s_waitcnt lgkmcnt(0)
	v_add_f32_e32 v0, v0, v1
	v_mov_b32_e32 v1, v0
	s_nop 1
	v_permlane32_swap_b32_e32 v1, v0
	s_and_saveexec_b64 s[4:5], vcc
	s_cbranch_execz .LBB0_1246
	v_lshl_add_u32 v2, v165, 4, s6
	s_waitcnt lgkmcnt(0)
	v_add_f32_e32 v0, v0, v1
	ds_write_b32 v2, v0
